# attention P.V segments: V fragments read 10-12 deep ahead of their MFMAs through a ring of free registers (same MFMA order)
# speedup vs baseline: 1.0030x; 1.0003x over previous
.Lstk_nm0:
	v_exp_f32_e64 v200, -|v66|
	v_exp_f32_e64 v201, -|v67|
	v_exp_f32_e64 v202, -|v68|
	v_exp_f32_e64 v203, -|v69|
	v_pk_add_f32 v[200:201], v[200:201], v[236:237] op_sel_hi:[1,0]
	v_max_i32_e32 v174, 0, v66
	v_max_i32_e32 v175, 0, v67
	v_log_f32_e32 v200, v200
	v_log_f32_e32 v201, v201
	v_exp_f32_e64 v204, -|v70|
	v_exp_f32_e64 v205, -|v71|
	v_pk_add_f32 v[202:203], v[202:203], v[236:237] op_sel_hi:[1,0]
	v_max_i32_e32 v176, 0, v68
	v_max_i32_e32 v177, 0, v69
	v_log_f32_e32 v202, v202
	v_log_f32_e32 v203, v203
	v_pk_add_f32 v[200:201], v[200:201], v[174:175]
	v_pk_add_f32 v[66:67], v[66:67], v[200:201] neg_lo:[0,1] neg_hi:[0,1]
	v_exp_f32_e64 v206, -|v72|
	v_exp_f32_e64 v207, -|v73|
	v_pk_add_f32 v[204:205], v[204:205], v[236:237] op_sel_hi:[1,0]
	v_max_i32_e32 v174, 0, v70
	v_max_i32_e32 v175, 0, v71
	v_log_f32_e32 v204, v204
	v_log_f32_e32 v205, v205
	v_pk_add_f32 v[202:203], v[202:203], v[176:177]
	v_pk_add_f32 v[68:69], v[68:69], v[202:203] neg_lo:[0,1] neg_hi:[0,1]
	v_exp_f32_e64 v208, -|v74|
	v_exp_f32_e64 v209, -|v75|
	v_pk_add_f32 v[206:207], v[206:207], v[236:237] op_sel_hi:[1,0]
	v_max_i32_e32 v176, 0, v72
	v_max_i32_e32 v177, 0, v73
	v_log_f32_e32 v206, v206
	v_log_f32_e32 v207, v207
	v_pk_add_f32 v[204:205], v[204:205], v[174:175]
	v_pk_add_f32 v[70:71], v[70:71], v[204:205] neg_lo:[0,1] neg_hi:[0,1]
	v_exp_f32_e64 v210, -|v76|
	v_exp_f32_e64 v211, -|v77|
	v_pk_add_f32 v[208:209], v[208:209], v[236:237] op_sel_hi:[1,0]
	v_max_i32_e32 v174, 0, v74
	v_max_i32_e32 v175, 0, v75
	v_log_f32_e32 v208, v208
	v_log_f32_e32 v209, v209
	v_pk_add_f32 v[206:207], v[206:207], v[176:177]
	v_pk_add_f32 v[72:73], v[72:73], v[206:207] neg_lo:[0,1] neg_hi:[0,1]
	v_exp_f32_e64 v212, -|v78|
	v_exp_f32_e64 v213, -|v79|
	v_pk_add_f32 v[210:211], v[210:211], v[236:237] op_sel_hi:[1,0]
	v_max_i32_e32 v176, 0, v76
	v_max_i32_e32 v177, 0, v77
	v_log_f32_e32 v210, v210
	v_log_f32_e32 v211, v211
	v_pk_add_f32 v[208:209], v[208:209], v[174:175]
	v_pk_add_f32 v[74:75], v[74:75], v[208:209] neg_lo:[0,1] neg_hi:[0,1]
	v_exp_f32_e64 v214, -|v80|
	v_exp_f32_e64 v215, -|v81|
	v_pk_add_f32 v[212:213], v[212:213], v[236:237] op_sel_hi:[1,0]
	v_max_i32_e32 v174, 0, v78
	v_max_i32_e32 v175, 0, v79
	v_log_f32_e32 v212, v212
	v_log_f32_e32 v213, v213
	v_pk_add_f32 v[210:211], v[210:211], v[176:177]
	v_pk_add_f32 v[76:77], v[76:77], v[210:211] neg_lo:[0,1] neg_hi:[0,1]
	v_pk_add_f32 v[214:215], v[214:215], v[236:237] op_sel_hi:[1,0]
	v_max_i32_e32 v176, 0, v80
	v_max_i32_e32 v177, 0, v81
	v_log_f32_e32 v214, v214
	v_log_f32_e32 v215, v215
	v_pk_add_f32 v[212:213], v[212:213], v[174:175]
	v_pk_add_f32 v[78:79], v[78:79], v[212:213] neg_lo:[0,1] neg_hi:[0,1]
	v_pk_add_f32 v[214:215], v[214:215], v[176:177]
	v_pk_add_f32 v[80:81], v[80:81], v[214:215] neg_lo:[0,1] neg_hi:[0,1]
	v_pk_add_f32 v[174:175], v[200:201], v[202:203]
	v_add_f32_e32 v216, v174, v175
	v_mov_b32_e32 v220, v216
	v_pk_add_f32 v[176:177], v[204:205], v[206:207]
	v_add_f32_e32 v217, v176, v177
	v_mov_b32_e32 v221, v217
	v_pk_add_f32 v[174:175], v[208:209], v[210:211]
	v_add_f32_e32 v218, v174, v175
	v_mov_b32_e32 v222, v218
	v_pk_add_f32 v[176:177], v[212:213], v[214:215]
	v_add_f32_e32 v219, v176, v177
	v_mov_b32_e32 v223, v219
	s_nop 1
	v_permlane32_swap_b32_e32 v216, v220
	v_permlane32_swap_b32_e32 v217, v221
	v_permlane32_swap_b32_e32 v218, v222
	v_permlane32_swap_b32_e32 v219, v223
	v_add_f32_e32 v216, v216, v220
	v_cndmask_b32_e64 v220, 0, v220, s[4:5]
	v_add_f32_e32 v217, v217, v221
	v_cndmask_b32_e64 v221, 0, v221, s[4:5]
	v_add_f32_e32 v218, v218, v222
	v_cndmask_b32_e64 v222, 0, v222, s[4:5]
	v_add_f32_e32 v219, v219, v223
	v_cndmask_b32_e64 v223, 0, v223, s[4:5]
	v_add_f32_e32 v224, v219, v218
	v_add_f32_e32 v225, v224, v217
	v_add_f32_e32 v230, v225, v216
	v_sub_f32_e32 v233, v182, v223
	v_sub_f32_e32 v232, v233, v215
	v_sub_f32_e32 v229, v232, v214
	v_sub_f32_e32 v228, v229, v213
	v_pk_add_f32 v[80:81], v[80:81], v[232:233]
	v_pk_add_f32 v[78:79], v[78:79], v[228:229]
	v_exp_f32_e32 v80, v80
	v_exp_f32_e32 v81, v81
	v_exp_f32_e32 v78, v78
	v_exp_f32_e32 v79, v79
	v_sub_f32_e32 v227, v182, v219
	v_sub_f32_e32 v177, v227, v222
	v_sub_f32_e32 v176, v177, v211
	v_sub_f32_e32 v235, v176, v210
	v_sub_f32_e32 v234, v235, v209
	v_pk_add_f32 v[76:77], v[76:77], v[176:177]
	v_pk_add_f32 v[74:75], v[74:75], v[234:235]
	v_exp_f32_e32 v76, v76
	v_exp_f32_e32 v77, v77
	v_exp_f32_e32 v74, v74
	v_exp_f32_e32 v75, v75
	v_sub_f32_e32 v226, v182, v224
	v_sub_f32_e32 v233, v226, v221
	v_sub_f32_e32 v232, v233, v207
	v_sub_f32_e32 v229, v232, v206
	v_sub_f32_e32 v228, v229, v205
	v_pk_add_f32 v[72:73], v[72:73], v[232:233]
	v_pk_add_f32 v[70:71], v[70:71], v[228:229]
	v_exp_f32_e32 v72, v72
	v_exp_f32_e32 v73, v73
	v_exp_f32_e32 v70, v70
	v_exp_f32_e32 v71, v71
	v_sub_f32_e32 v227, v182, v225
	v_sub_f32_e32 v177, v227, v220
	v_sub_f32_e32 v176, v177, v203
	v_sub_f32_e32 v235, v176, v202
	v_sub_f32_e32 v234, v235, v201
	v_pk_add_f32 v[68:69], v[68:69], v[176:177]
	v_pk_add_f32 v[66:67], v[66:67], v[234:235]
	v_exp_f32_e32 v68, v68
	v_exp_f32_e32 v69, v69
	v_exp_f32_e32 v66, v66
	v_exp_f32_e32 v67, v67
	v_add_f32_e64 v173, -v183, -v230
	v_add_u32_e32 v0, v0, v191
	v_cvt_pk_bf16_f32 v66, v66, v67
	v_cvt_pk_bf16_f32 v67, v68, v69
	v_cvt_pk_bf16_f32 v68, v70, v71
	v_cvt_pk_bf16_f32 v69, v72, v73
	v_cvt_pk_bf16_f32 v70, v74, v75
	v_cvt_pk_bf16_f32 v71, v76, v77
	v_cvt_pk_bf16_f32 v72, v78, v79
	v_cvt_pk_bf16_f32 v73, v80, v81
	v_cvt_pk_bf16_f32 v74, v82, v83
	v_cvt_pk_bf16_f32 v75, v84, v85
	v_cvt_pk_bf16_f32 v76, v86, v87
	v_cvt_pk_bf16_f32 v77, v88, v89
	v_cvt_pk_bf16_f32 v78, v90, v91
	v_cvt_pk_bf16_f32 v79, v92, v93
	v_cvt_pk_bf16_f32 v80, v94, v95
	v_cvt_pk_bf16_f32 v81, v96, v97
	ds_read_b128 v[82:85], v0 offset:17408
	ds_read_b128 v[86:89], v0 offset:22016
	ds_read_b128 v[90:93], v0 offset:26624
	ds_read_b128 v[94:97], v0 offset:31232
	ds_read_b128 v[200:203], v0 offset:17440
	ds_read_b128 v[204:207], v0 offset:22048
	ds_read_b128 v[208:211], v0 offset:26656
	ds_read_b128 v[212:215], v0 offset:31264
	ds_read_b128 v[216:219], v0 offset:17472
	ds_read_b128 v[220:223], v0 offset:22080
	ds_read_b128 v[224:227], v0 offset:26688
	s_setprio 1
	s_waitcnt lgkmcnt(10)
	v_mfma_f32_32x32x16_bf16 v[50:65], v[82:85], v[66:69], v[50:65]
	ds_read_b128 v[82:85], v0 offset:31296
	s_waitcnt lgkmcnt(10)
	v_mfma_f32_32x32x16_bf16 v[34:49], v[86:89], v[66:69], v[34:49]
	ds_read_b128 v[86:89], v0 offset:17504
	s_waitcnt lgkmcnt(10)
	v_mfma_f32_32x32x16_bf16 v[18:33], v[90:93], v[66:69], v[18:33]
	ds_read_b128 v[90:93], v0 offset:22112
	s_waitcnt lgkmcnt(10)
	v_mfma_f32_32x32x16_bf16 v[2:17], v[94:97], v[66:69], v[2:17]
	ds_read_b128 v[94:97], v0 offset:26720
	s_waitcnt lgkmcnt(10)
	v_mfma_f32_32x32x16_bf16 v[50:65], v[200:203], v[70:73], v[50:65]
	ds_read_b128 v[200:203], v0 offset:31328
	s_waitcnt lgkmcnt(10)
	v_mfma_f32_32x32x16_bf16 v[34:49], v[204:207], v[70:73], v[34:49]
	s_waitcnt lgkmcnt(9)
	v_mfma_f32_32x32x16_bf16 v[18:33], v[208:211], v[70:73], v[18:33]
	s_waitcnt lgkmcnt(8)
	v_mfma_f32_32x32x16_bf16 v[2:17], v[212:215], v[70:73], v[2:17]
	s_waitcnt lgkmcnt(7)
	v_mfma_f32_32x32x16_bf16 v[50:65], v[216:219], v[74:77], v[50:65]
	s_waitcnt lgkmcnt(6)
	v_mfma_f32_32x32x16_bf16 v[34:49], v[220:223], v[74:77], v[34:49]
	s_waitcnt lgkmcnt(5)
	v_mfma_f32_32x32x16_bf16 v[18:33], v[224:227], v[74:77], v[18:33]
	s_waitcnt lgkmcnt(4)
	v_mfma_f32_32x32x16_bf16 v[2:17], v[82:85], v[74:77], v[2:17]
	s_waitcnt lgkmcnt(3)
	v_mfma_f32_32x32x16_bf16 v[50:65], v[86:89], v[78:81], v[50:65]
	s_waitcnt lgkmcnt(2)
	v_mfma_f32_32x32x16_bf16 v[34:49], v[90:93], v[78:81], v[34:49]
	s_waitcnt lgkmcnt(1)
	v_mfma_f32_32x32x16_bf16 v[18:33], v[94:97], v[78:81], v[18:33]
	s_waitcnt lgkmcnt(0)
	v_mfma_f32_32x32x16_bf16 v[2:17], v[200:203], v[78:81], v[2:17]
	s_setprio 0
	v_add_f32_e32 v172, v172, v173

.LBB0_70:
	v_pk_add_f32 v[66:67], v[66:67], v[202:203] op_sel:[0,1] op_sel_hi:[1,1] neg_lo:[0,1] neg_hi:[0,1]
	v_pk_add_f32 v[82:83], v[82:83], v[202:203] op_sel:[0,1] op_sel_hi:[1,1] neg_lo:[0,1] neg_hi:[0,1]
	v_exp_f32_e32 v66, v66
	v_exp_f32_e32 v67, v67
	v_exp_f32_e32 v82, v82
	v_exp_f32_e32 v83, v83
	v_pk_add_f32 v[68:69], v[68:69], v[202:203] op_sel:[0,1] op_sel_hi:[1,1] neg_lo:[0,1] neg_hi:[0,1]
	v_pk_add_f32 v[84:85], v[84:85], v[202:203] op_sel:[0,1] op_sel_hi:[1,1] neg_lo:[0,1] neg_hi:[0,1]
	v_exp_f32_e32 v68, v68
	v_exp_f32_e32 v69, v69
	v_exp_f32_e32 v84, v84
	v_exp_f32_e32 v85, v85
	v_pk_add_f32 v[174:175], v[66:67], v[82:83]
	v_pk_add_f32 v[70:71], v[70:71], v[202:203] op_sel:[0,1] op_sel_hi:[1,1] neg_lo:[0,1] neg_hi:[0,1]
	v_pk_add_f32 v[86:87], v[86:87], v[202:203] op_sel:[0,1] op_sel_hi:[1,1] neg_lo:[0,1] neg_hi:[0,1]
	v_exp_f32_e32 v70, v70
	v_exp_f32_e32 v71, v71
	v_exp_f32_e32 v86, v86
	v_exp_f32_e32 v87, v87
	v_pk_add_f32 v[174:175], v[174:175], v[68:69]
	v_pk_add_f32 v[174:175], v[174:175], v[84:85]
	v_pk_add_f32 v[72:73], v[72:73], v[202:203] op_sel:[0,1] op_sel_hi:[1,1] neg_lo:[0,1] neg_hi:[0,1]
	v_pk_add_f32 v[88:89], v[88:89], v[202:203] op_sel:[0,1] op_sel_hi:[1,1] neg_lo:[0,1] neg_hi:[0,1]
	v_exp_f32_e32 v72, v72
	v_exp_f32_e32 v73, v73
	v_exp_f32_e32 v88, v88
	v_exp_f32_e32 v89, v89
	v_pk_add_f32 v[174:175], v[174:175], v[70:71]
	v_pk_add_f32 v[174:175], v[174:175], v[86:87]
	v_pk_add_f32 v[74:75], v[74:75], v[202:203] op_sel:[0,1] op_sel_hi:[1,1] neg_lo:[0,1] neg_hi:[0,1]
	v_pk_add_f32 v[90:91], v[90:91], v[202:203] op_sel:[0,1] op_sel_hi:[1,1] neg_lo:[0,1] neg_hi:[0,1]
	v_exp_f32_e32 v74, v74
	v_exp_f32_e32 v75, v75
	v_exp_f32_e32 v90, v90
	v_exp_f32_e32 v91, v91
	v_pk_add_f32 v[174:175], v[174:175], v[72:73]
	v_pk_add_f32 v[174:175], v[174:175], v[88:89]
	v_pk_add_f32 v[76:77], v[76:77], v[202:203] op_sel:[0,1] op_sel_hi:[1,1] neg_lo:[0,1] neg_hi:[0,1]
	v_pk_add_f32 v[92:93], v[92:93], v[202:203] op_sel:[0,1] op_sel_hi:[1,1] neg_lo:[0,1] neg_hi:[0,1]
	v_exp_f32_e32 v76, v76
	v_exp_f32_e32 v77, v77
	v_exp_f32_e32 v92, v92
	v_exp_f32_e32 v93, v93
	v_pk_add_f32 v[174:175], v[174:175], v[74:75]
	v_pk_add_f32 v[174:175], v[174:175], v[90:91]
	v_pk_add_f32 v[78:79], v[78:79], v[202:203] op_sel:[0,1] op_sel_hi:[1,1] neg_lo:[0,1] neg_hi:[0,1]
	v_pk_add_f32 v[94:95], v[94:95], v[202:203] op_sel:[0,1] op_sel_hi:[1,1] neg_lo:[0,1] neg_hi:[0,1]
	v_exp_f32_e32 v78, v78
	v_exp_f32_e32 v79, v79
	v_exp_f32_e32 v94, v94
	v_exp_f32_e32 v95, v95
	v_pk_add_f32 v[174:175], v[174:175], v[76:77]
	v_pk_add_f32 v[174:175], v[174:175], v[92:93]
	v_pk_add_f32 v[80:81], v[80:81], v[202:203] op_sel:[0,1] op_sel_hi:[1,1] neg_lo:[0,1] neg_hi:[0,1]
	v_pk_add_f32 v[96:97], v[96:97], v[202:203] op_sel:[0,1] op_sel_hi:[1,1] neg_lo:[0,1] neg_hi:[0,1]
	v_exp_f32_e32 v80, v80
	v_exp_f32_e32 v81, v81
	v_exp_f32_e32 v96, v96
	v_exp_f32_e32 v97, v97
	v_pk_add_f32 v[174:175], v[174:175], v[78:79]
	v_pk_add_f32 v[174:175], v[174:175], v[94:95]
	s_nop 0
	v_pk_add_f32 v[174:175], v[174:175], v[80:81]
	v_pk_add_f32 v[174:175], v[174:175], v[96:97]
	v_add_f32_e32 v216, v174, v175
	v_fmac_f32_e32 v216, v193, v202
	v_add3_u32 v193, s47, v210, v211
	v_cvt_pk_bf16_f32 v174, v66, v67
	v_cvt_pk_bf16_f32 v175, v68, v69
	v_cvt_pk_bf16_f32 v176, v70, v71
	v_cvt_pk_bf16_f32 v177, v72, v73
	v_cvt_pk_bf16_f32 v218, v74, v75
	v_cvt_pk_bf16_f32 v219, v76, v77
	v_cvt_pk_bf16_f32 v220, v78, v79
	v_cvt_pk_bf16_f32 v221, v80, v81
	v_cvt_pk_bf16_f32 v222, v82, v83
	v_cvt_pk_bf16_f32 v223, v84, v85
	v_cvt_pk_bf16_f32 v224, v86, v87
	v_cvt_pk_bf16_f32 v225, v88, v89
	v_cvt_pk_bf16_f32 v226, v90, v91
	v_cvt_pk_bf16_f32 v227, v92, v93
	v_cvt_pk_bf16_f32 v228, v94, v95
	v_cvt_pk_bf16_f32 v229, v96, v97
	ds_read_b128 v[232:235], v193 offset:17408
	ds_read_b128 v[236:239], v193 offset:22016
	ds_read_b128 v[240:243], v193 offset:26624
	ds_read_b128 v[248:251], v193 offset:31232
	ds_read_b128 v[66:69], v193 offset:17440
	ds_read_b128 v[70:73], v193 offset:22048
	ds_read_b128 v[74:77], v193 offset:26656
	ds_read_b128 v[78:81], v193 offset:31264
	ds_read_b128 v[82:85], v193 offset:17472
	ds_read_b128 v[86:89], v193 offset:22080
	ds_read_b128 v[90:93], v193 offset:26688
	ds_read_b128 v[94:97], v193 offset:31296
	s_setprio 1
	s_waitcnt lgkmcnt(11)
	v_mfma_f32_32x32x16_bf16 v[50:65], v[232:235], v[174:177], v[50:65]
	ds_read_b128 v[232:235], v193 offset:17504
	s_waitcnt lgkmcnt(11)
	v_mfma_f32_32x32x16_bf16 v[34:49], v[236:239], v[174:177], v[34:49]
	ds_read_b128 v[236:239], v193 offset:22112
	s_waitcnt lgkmcnt(11)
	v_mfma_f32_32x32x16_bf16 v[18:33], v[240:243], v[174:177], v[18:33]
	ds_read_b128 v[240:243], v193 offset:26720
	s_waitcnt lgkmcnt(11)
	v_mfma_f32_32x32x16_bf16 v[2:17], v[248:251], v[174:177], v[2:17]
	ds_read_b128 v[248:251], v193 offset:31328
	s_waitcnt lgkmcnt(11)
	v_mfma_f32_32x32x16_bf16 v[50:65], v[66:69], v[218:221], v[50:65]
	s_waitcnt lgkmcnt(10)
	v_mfma_f32_32x32x16_bf16 v[34:49], v[70:73], v[218:221], v[34:49]
	s_waitcnt lgkmcnt(9)
	v_mfma_f32_32x32x16_bf16 v[18:33], v[74:77], v[218:221], v[18:33]
	s_waitcnt lgkmcnt(8)
	v_mfma_f32_32x32x16_bf16 v[2:17], v[78:81], v[218:221], v[2:17]
	s_waitcnt lgkmcnt(7)
	v_mfma_f32_32x32x16_bf16 v[50:65], v[82:85], v[222:225], v[50:65]
	s_waitcnt lgkmcnt(6)
	v_mfma_f32_32x32x16_bf16 v[34:49], v[86:89], v[222:225], v[34:49]
	s_waitcnt lgkmcnt(5)
	v_mfma_f32_32x32x16_bf16 v[18:33], v[90:93], v[222:225], v[18:33]
	s_waitcnt lgkmcnt(4)
	v_mfma_f32_32x32x16_bf16 v[2:17], v[94:97], v[222:225], v[2:17]
	s_waitcnt lgkmcnt(3)
	v_mfma_f32_32x32x16_bf16 v[50:65], v[232:235], v[226:229], v[50:65]
	s_waitcnt lgkmcnt(2)
	v_mfma_f32_32x32x16_bf16 v[34:49], v[236:239], v[226:229], v[34:49]
	s_waitcnt lgkmcnt(1)
	v_mfma_f32_32x32x16_bf16 v[18:33], v[240:243], v[226:229], v[18:33]
	s_waitcnt lgkmcnt(0)
	v_mfma_f32_32x32x16_bf16 v[2:17], v[248:251], v[226:229], v[2:17]
	s_setprio 0

.LBB0_75:
	v_pk_add_f32 v[66:67], v[66:67], v[216:217] op_sel_hi:[1,0] neg_lo:[0,1] neg_hi:[0,1]
	v_pk_add_f32 v[82:83], v[82:83], v[216:217] op_sel_hi:[1,0] neg_lo:[0,1] neg_hi:[0,1]
	v_exp_f32_e32 v66, v66
	v_exp_f32_e32 v67, v67
	v_exp_f32_e32 v82, v82
	v_exp_f32_e32 v83, v83
	v_pk_add_f32 v[68:69], v[68:69], v[216:217] op_sel_hi:[1,0] neg_lo:[0,1] neg_hi:[0,1]
	v_pk_add_f32 v[84:85], v[84:85], v[216:217] op_sel_hi:[1,0] neg_lo:[0,1] neg_hi:[0,1]
	v_exp_f32_e32 v68, v68
	v_exp_f32_e32 v69, v69
	v_exp_f32_e32 v84, v84
	v_exp_f32_e32 v85, v85
	v_pk_add_f32 v[174:175], v[66:67], v[82:83]
	v_pk_add_f32 v[70:71], v[70:71], v[216:217] op_sel_hi:[1,0] neg_lo:[0,1] neg_hi:[0,1]
	v_pk_add_f32 v[86:87], v[86:87], v[216:217] op_sel_hi:[1,0] neg_lo:[0,1] neg_hi:[0,1]
	v_exp_f32_e32 v70, v70
	v_exp_f32_e32 v71, v71
	v_exp_f32_e32 v86, v86
	v_exp_f32_e32 v87, v87
	v_pk_add_f32 v[174:175], v[174:175], v[68:69]
	v_pk_add_f32 v[174:175], v[174:175], v[84:85]
	v_pk_add_f32 v[72:73], v[72:73], v[216:217] op_sel_hi:[1,0] neg_lo:[0,1] neg_hi:[0,1]
	v_pk_add_f32 v[88:89], v[88:89], v[216:217] op_sel_hi:[1,0] neg_lo:[0,1] neg_hi:[0,1]
	v_exp_f32_e32 v72, v72
	v_exp_f32_e32 v73, v73
	v_exp_f32_e32 v88, v88
	v_exp_f32_e32 v89, v89
	v_pk_add_f32 v[174:175], v[174:175], v[70:71]
	v_pk_add_f32 v[174:175], v[174:175], v[86:87]
	v_pk_add_f32 v[74:75], v[74:75], v[216:217] op_sel_hi:[1,0] neg_lo:[0,1] neg_hi:[0,1]
	v_pk_add_f32 v[90:91], v[90:91], v[216:217] op_sel_hi:[1,0] neg_lo:[0,1] neg_hi:[0,1]
	v_exp_f32_e32 v74, v74
	v_exp_f32_e32 v75, v75
	v_exp_f32_e32 v90, v90
	v_exp_f32_e32 v91, v91
	v_pk_add_f32 v[174:175], v[174:175], v[72:73]
	v_pk_add_f32 v[174:175], v[174:175], v[88:89]
	v_pk_add_f32 v[76:77], v[76:77], v[216:217] op_sel_hi:[1,0] neg_lo:[0,1] neg_hi:[0,1]
	v_pk_add_f32 v[92:93], v[92:93], v[216:217] op_sel_hi:[1,0] neg_lo:[0,1] neg_hi:[0,1]
	v_exp_f32_e32 v76, v76
	v_exp_f32_e32 v77, v77
	v_exp_f32_e32 v92, v92
	v_exp_f32_e32 v93, v93
	v_pk_add_f32 v[174:175], v[174:175], v[74:75]
	v_pk_add_f32 v[174:175], v[174:175], v[90:91]
	v_pk_add_f32 v[78:79], v[78:79], v[216:217] op_sel_hi:[1,0] neg_lo:[0,1] neg_hi:[0,1]
	v_pk_add_f32 v[94:95], v[94:95], v[216:217] op_sel_hi:[1,0] neg_lo:[0,1] neg_hi:[0,1]
	v_exp_f32_e32 v78, v78
	v_exp_f32_e32 v79, v79
	v_exp_f32_e32 v94, v94
	v_exp_f32_e32 v95, v95
	v_pk_add_f32 v[174:175], v[174:175], v[76:77]
	v_pk_add_f32 v[174:175], v[174:175], v[92:93]
	v_pk_add_f32 v[80:81], v[80:81], v[216:217] op_sel_hi:[1,0] neg_lo:[0,1] neg_hi:[0,1]
	v_pk_add_f32 v[96:97], v[96:97], v[216:217] op_sel_hi:[1,0] neg_lo:[0,1] neg_hi:[0,1]
	v_exp_f32_e32 v80, v80
	v_exp_f32_e32 v81, v81
	v_exp_f32_e32 v96, v96
	v_exp_f32_e32 v97, v97
	v_pk_add_f32 v[174:175], v[174:175], v[78:79]
	v_pk_add_f32 v[174:175], v[174:175], v[94:95]
	s_mul_i32 s48, s48, 0x8c00
	s_nop 0
	v_pk_add_f32 v[174:175], v[174:175], v[80:81]
	v_pk_add_f32 v[174:175], v[174:175], v[96:97]
	v_add_f32_e32 v216, v174, v175
	v_add_u32_e32 v174, s48, v212
	v_cvt_pk_bf16_f32 v66, v66, v67
	v_cvt_pk_bf16_f32 v67, v68, v69
	v_cvt_pk_bf16_f32 v68, v70, v71
	v_cvt_pk_bf16_f32 v69, v72, v73
	v_cvt_pk_bf16_f32 v70, v74, v75
	v_cvt_pk_bf16_f32 v71, v76, v77
	v_cvt_pk_bf16_f32 v72, v78, v79
	v_cvt_pk_bf16_f32 v73, v80, v81
	v_cvt_pk_bf16_f32 v74, v82, v83
	v_cvt_pk_bf16_f32 v75, v84, v85
	v_cvt_pk_bf16_f32 v76, v86, v87
	v_cvt_pk_bf16_f32 v77, v88, v89
	v_cvt_pk_bf16_f32 v78, v90, v91
	v_cvt_pk_bf16_f32 v79, v92, v93
	v_cvt_pk_bf16_f32 v80, v94, v95
	v_cvt_pk_bf16_f32 v81, v96, v97
	ds_read_b128 v[82:85], v174 offset:17408
	ds_read_b128 v[86:89], v174 offset:22016
	ds_read_b128 v[90:93], v174 offset:26624
	ds_read_b128 v[94:97], v174 offset:31232
	ds_read_b128 v[220:223], v174 offset:17440
	ds_read_b128 v[224:227], v174 offset:22048
	ds_read_b128 v[232:235], v174 offset:26656
	ds_read_b128 v[236:239], v174 offset:31264
	ds_read_b128 v[240:243], v174 offset:17472
	ds_read_b128 v[248:251], v174 offset:22080
	v_fmac_f32_e32 v216, v193, v202
	s_setprio 1
	s_waitcnt lgkmcnt(9)
	v_mfma_f32_32x32x16_bf16 v[50:65], v[82:85], v[66:69], v[50:65]
	ds_read_b128 v[82:85], v174 offset:26688
	s_waitcnt lgkmcnt(9)
	v_mfma_f32_32x32x16_bf16 v[34:49], v[86:89], v[66:69], v[34:49]
	ds_read_b128 v[86:89], v174 offset:31296
	s_waitcnt lgkmcnt(9)
	v_mfma_f32_32x32x16_bf16 v[18:33], v[90:93], v[66:69], v[18:33]
	ds_read_b128 v[90:93], v174 offset:17504
	s_waitcnt lgkmcnt(9)
	v_mfma_f32_32x32x16_bf16 v[2:17], v[94:97], v[66:69], v[2:17]
	ds_read_b128 v[94:97], v174 offset:22112
	s_waitcnt lgkmcnt(9)
	v_mfma_f32_32x32x16_bf16 v[50:65], v[220:223], v[70:73], v[50:65]
	ds_read_b128 v[220:223], v174 offset:26720
	s_waitcnt lgkmcnt(9)
	v_mfma_f32_32x32x16_bf16 v[34:49], v[224:227], v[70:73], v[34:49]
	ds_read_b128 v[224:227], v174 offset:31328
	s_waitcnt lgkmcnt(9)
	v_mfma_f32_32x32x16_bf16 v[18:33], v[232:235], v[70:73], v[18:33]
	s_waitcnt lgkmcnt(8)
	v_mfma_f32_32x32x16_bf16 v[2:17], v[236:239], v[70:73], v[2:17]
	s_waitcnt lgkmcnt(7)
	v_mfma_f32_32x32x16_bf16 v[50:65], v[240:243], v[74:77], v[50:65]
	s_waitcnt lgkmcnt(6)
	v_mfma_f32_32x32x16_bf16 v[34:49], v[248:251], v[74:77], v[34:49]
	s_waitcnt lgkmcnt(5)
	v_mfma_f32_32x32x16_bf16 v[18:33], v[82:85], v[74:77], v[18:33]
	s_waitcnt lgkmcnt(4)
	v_mfma_f32_32x32x16_bf16 v[2:17], v[86:89], v[74:77], v[2:17]
	s_waitcnt lgkmcnt(3)
	v_mfma_f32_32x32x16_bf16 v[50:65], v[90:93], v[78:81], v[50:65]
	s_waitcnt lgkmcnt(2)
	v_mfma_f32_32x32x16_bf16 v[34:49], v[94:97], v[78:81], v[34:49]
	s_waitcnt lgkmcnt(1)
	v_mfma_f32_32x32x16_bf16 v[18:33], v[220:223], v[78:81], v[18:33]
	s_waitcnt lgkmcnt(0)
	v_mfma_f32_32x32x16_bf16 v[2:17], v[224:227], v[78:81], v[2:17]
	s_setprio 0
	s_branch .LBB0_77

.LBB0_92:
	v_pk_add_f32 v[66:67], v[66:67], v[192:193] op_sel:[0,1] op_sel_hi:[1,1] neg_lo:[0,1] neg_hi:[0,1]
	v_pk_add_f32 v[82:83], v[82:83], v[192:193] op_sel:[0,1] op_sel_hi:[1,1] neg_lo:[0,1] neg_hi:[0,1]
	v_exp_f32_e32 v66, v66
	v_exp_f32_e32 v67, v67
	v_exp_f32_e32 v82, v82
	v_exp_f32_e32 v83, v83
	v_pk_add_f32 v[68:69], v[68:69], v[192:193] op_sel:[0,1] op_sel_hi:[1,1] neg_lo:[0,1] neg_hi:[0,1]
	v_pk_add_f32 v[84:85], v[84:85], v[192:193] op_sel:[0,1] op_sel_hi:[1,1] neg_lo:[0,1] neg_hi:[0,1]
	v_exp_f32_e32 v68, v68
	v_exp_f32_e32 v69, v69
	v_exp_f32_e32 v84, v84
	v_exp_f32_e32 v85, v85
	v_pk_add_f32 v[174:175], v[66:67], v[82:83]
	v_pk_add_f32 v[70:71], v[70:71], v[192:193] op_sel:[0,1] op_sel_hi:[1,1] neg_lo:[0,1] neg_hi:[0,1]
	v_pk_add_f32 v[86:87], v[86:87], v[192:193] op_sel:[0,1] op_sel_hi:[1,1] neg_lo:[0,1] neg_hi:[0,1]
	v_exp_f32_e32 v70, v70
	v_exp_f32_e32 v71, v71
	v_exp_f32_e32 v86, v86
	v_exp_f32_e32 v87, v87
	v_pk_add_f32 v[174:175], v[174:175], v[68:69]
	v_pk_add_f32 v[174:175], v[174:175], v[84:85]
	v_pk_add_f32 v[72:73], v[72:73], v[192:193] op_sel:[0,1] op_sel_hi:[1,1] neg_lo:[0,1] neg_hi:[0,1]
	v_pk_add_f32 v[88:89], v[88:89], v[192:193] op_sel:[0,1] op_sel_hi:[1,1] neg_lo:[0,1] neg_hi:[0,1]
	v_exp_f32_e32 v72, v72
	v_exp_f32_e32 v73, v73
	v_exp_f32_e32 v88, v88
	v_exp_f32_e32 v89, v89
	v_pk_add_f32 v[174:175], v[174:175], v[70:71]
	v_pk_add_f32 v[174:175], v[174:175], v[86:87]
	v_pk_add_f32 v[74:75], v[74:75], v[192:193] op_sel:[0,1] op_sel_hi:[1,1] neg_lo:[0,1] neg_hi:[0,1]
	v_pk_add_f32 v[90:91], v[90:91], v[192:193] op_sel:[0,1] op_sel_hi:[1,1] neg_lo:[0,1] neg_hi:[0,1]
	v_exp_f32_e32 v74, v74
	v_exp_f32_e32 v75, v75
	v_exp_f32_e32 v90, v90
	v_exp_f32_e32 v91, v91
	v_pk_add_f32 v[174:175], v[174:175], v[72:73]
	v_pk_add_f32 v[174:175], v[174:175], v[88:89]
	v_pk_add_f32 v[76:77], v[76:77], v[192:193] op_sel:[0,1] op_sel_hi:[1,1] neg_lo:[0,1] neg_hi:[0,1]
	v_pk_add_f32 v[92:93], v[92:93], v[192:193] op_sel:[0,1] op_sel_hi:[1,1] neg_lo:[0,1] neg_hi:[0,1]
	v_exp_f32_e32 v76, v76
	v_exp_f32_e32 v77, v77
	v_exp_f32_e32 v92, v92
	v_exp_f32_e32 v93, v93
	v_pk_add_f32 v[174:175], v[174:175], v[74:75]
	v_pk_add_f32 v[174:175], v[174:175], v[90:91]
	v_pk_add_f32 v[78:79], v[78:79], v[192:193] op_sel:[0,1] op_sel_hi:[1,1] neg_lo:[0,1] neg_hi:[0,1]
	v_pk_add_f32 v[94:95], v[94:95], v[192:193] op_sel:[0,1] op_sel_hi:[1,1] neg_lo:[0,1] neg_hi:[0,1]
	v_exp_f32_e32 v78, v78
	v_exp_f32_e32 v79, v79
	v_exp_f32_e32 v94, v94
	v_exp_f32_e32 v95, v95
	v_pk_add_f32 v[174:175], v[174:175], v[76:77]
	v_pk_add_f32 v[174:175], v[174:175], v[92:93]
	v_pk_add_f32 v[80:81], v[80:81], v[192:193] op_sel:[0,1] op_sel_hi:[1,1] neg_lo:[0,1] neg_hi:[0,1]
	v_pk_add_f32 v[96:97], v[96:97], v[192:193] op_sel:[0,1] op_sel_hi:[1,1] neg_lo:[0,1] neg_hi:[0,1]
	v_exp_f32_e32 v80, v80
	v_exp_f32_e32 v81, v81
	v_exp_f32_e32 v96, v96
	v_exp_f32_e32 v97, v97
	v_pk_add_f32 v[174:175], v[174:175], v[78:79]
	v_pk_add_f32 v[174:175], v[174:175], v[94:95]
	s_nop 0
	v_pk_add_f32 v[174:175], v[174:175], v[80:81]
	v_pk_add_f32 v[174:175], v[174:175], v[96:97]
	v_add_f32_e32 v193, v174, v175
	v_fmac_f32_e32 v193, v216, v204
	v_add3_u32 v204, s30, v210, v211
	v_cvt_pk_bf16_f32 v174, v66, v67
	v_cvt_pk_bf16_f32 v175, v68, v69
	v_cvt_pk_bf16_f32 v176, v70, v71
	v_cvt_pk_bf16_f32 v177, v72, v73
	v_cvt_pk_bf16_f32 v216, v74, v75
	v_cvt_pk_bf16_f32 v217, v76, v77
	v_cvt_pk_bf16_f32 v218, v78, v79
	v_cvt_pk_bf16_f32 v219, v80, v81
	v_cvt_pk_bf16_f32 v220, v82, v83
	v_cvt_pk_bf16_f32 v221, v84, v85
	v_cvt_pk_bf16_f32 v222, v86, v87
	v_cvt_pk_bf16_f32 v223, v88, v89
	v_cvt_pk_bf16_f32 v224, v90, v91
	v_cvt_pk_bf16_f32 v225, v92, v93
	v_cvt_pk_bf16_f32 v226, v94, v95
	v_cvt_pk_bf16_f32 v227, v96, v97
	ds_read_b128 v[232:235], v204 offset:17408
	ds_read_b128 v[236:239], v204 offset:22016
	ds_read_b128 v[240:243], v204 offset:26624
	ds_read_b128 v[248:251], v204 offset:31232
	ds_read_b128 v[66:69], v204 offset:17440
	ds_read_b128 v[70:73], v204 offset:22048
	ds_read_b128 v[74:77], v204 offset:26656
	ds_read_b128 v[78:81], v204 offset:31264
	ds_read_b128 v[82:85], v204 offset:17472
	ds_read_b128 v[86:89], v204 offset:22080
	ds_read_b128 v[90:93], v204 offset:26688
	ds_read_b128 v[94:97], v204 offset:31296
	s_setprio 1
	s_waitcnt lgkmcnt(11)
	v_mfma_f32_32x32x16_bf16 v[50:65], v[232:235], v[174:177], v[50:65]
	ds_read_b128 v[232:235], v204 offset:17504
	s_waitcnt lgkmcnt(11)
	v_mfma_f32_32x32x16_bf16 v[34:49], v[236:239], v[174:177], v[34:49]
	ds_read_b128 v[236:239], v204 offset:22112
	s_waitcnt lgkmcnt(11)
	v_mfma_f32_32x32x16_bf16 v[18:33], v[240:243], v[174:177], v[18:33]
	ds_read_b128 v[240:243], v204 offset:26720
	s_waitcnt lgkmcnt(11)
	v_mfma_f32_32x32x16_bf16 v[2:17], v[248:251], v[174:177], v[2:17]
	ds_read_b128 v[248:251], v204 offset:31328
	s_waitcnt lgkmcnt(11)
	v_mfma_f32_32x32x16_bf16 v[50:65], v[66:69], v[216:219], v[50:65]
	s_waitcnt lgkmcnt(10)
	v_mfma_f32_32x32x16_bf16 v[34:49], v[70:73], v[216:219], v[34:49]
	s_waitcnt lgkmcnt(9)
	v_mfma_f32_32x32x16_bf16 v[18:33], v[74:77], v[216:219], v[18:33]
	s_waitcnt lgkmcnt(8)
	v_mfma_f32_32x32x16_bf16 v[2:17], v[78:81], v[216:219], v[2:17]
	s_waitcnt lgkmcnt(7)
	v_mfma_f32_32x32x16_bf16 v[50:65], v[82:85], v[220:223], v[50:65]
	s_waitcnt lgkmcnt(6)
	v_mfma_f32_32x32x16_bf16 v[34:49], v[86:89], v[220:223], v[34:49]
	s_waitcnt lgkmcnt(5)
	v_mfma_f32_32x32x16_bf16 v[18:33], v[90:93], v[220:223], v[18:33]
	s_waitcnt lgkmcnt(4)
	v_mfma_f32_32x32x16_bf16 v[2:17], v[94:97], v[220:223], v[2:17]
	s_waitcnt lgkmcnt(3)
	v_mfma_f32_32x32x16_bf16 v[50:65], v[232:235], v[224:227], v[50:65]
	s_waitcnt lgkmcnt(2)
	v_mfma_f32_32x32x16_bf16 v[34:49], v[236:239], v[224:227], v[34:49]
	s_waitcnt lgkmcnt(1)
	v_mfma_f32_32x32x16_bf16 v[18:33], v[240:243], v[224:227], v[18:33]
	s_waitcnt lgkmcnt(0)
	v_mfma_f32_32x32x16_bf16 v[2:17], v[248:251], v[224:227], v[2:17]
	s_setprio 0
	s_andn2_saveexec_b64 s[0:1], s[0:1]
	s_cbranch_execz .LBB0_87

.LBB0_95:
	v_pk_add_f32 v[66:67], v[66:67], v[192:193] op_sel:[0,1] op_sel_hi:[1,1] neg_lo:[0,1] neg_hi:[0,1]
	v_pk_add_f32 v[82:83], v[82:83], v[192:193] op_sel:[0,1] op_sel_hi:[1,1] neg_lo:[0,1] neg_hi:[0,1]
	v_exp_f32_e32 v66, v66
	v_exp_f32_e32 v67, v67
	v_exp_f32_e32 v82, v82
	v_exp_f32_e32 v83, v83
	v_pk_add_f32 v[68:69], v[68:69], v[192:193] op_sel:[0,1] op_sel_hi:[1,1] neg_lo:[0,1] neg_hi:[0,1]
	v_pk_add_f32 v[84:85], v[84:85], v[192:193] op_sel:[0,1] op_sel_hi:[1,1] neg_lo:[0,1] neg_hi:[0,1]
	v_exp_f32_e32 v68, v68
	v_exp_f32_e32 v69, v69
	v_exp_f32_e32 v84, v84
	v_exp_f32_e32 v85, v85
	v_pk_add_f32 v[174:175], v[66:67], v[82:83]
	v_pk_add_f32 v[70:71], v[70:71], v[192:193] op_sel:[0,1] op_sel_hi:[1,1] neg_lo:[0,1] neg_hi:[0,1]
	v_pk_add_f32 v[86:87], v[86:87], v[192:193] op_sel:[0,1] op_sel_hi:[1,1] neg_lo:[0,1] neg_hi:[0,1]
	v_exp_f32_e32 v70, v70
	v_exp_f32_e32 v71, v71
	v_exp_f32_e32 v86, v86
	v_exp_f32_e32 v87, v87
	v_pk_add_f32 v[174:175], v[174:175], v[68:69]
	v_pk_add_f32 v[174:175], v[174:175], v[84:85]
	v_pk_add_f32 v[72:73], v[72:73], v[192:193] op_sel:[0,1] op_sel_hi:[1,1] neg_lo:[0,1] neg_hi:[0,1]
	v_pk_add_f32 v[88:89], v[88:89], v[192:193] op_sel:[0,1] op_sel_hi:[1,1] neg_lo:[0,1] neg_hi:[0,1]
	v_exp_f32_e32 v72, v72
	v_exp_f32_e32 v73, v73
	v_exp_f32_e32 v88, v88
	v_exp_f32_e32 v89, v89
	v_pk_add_f32 v[174:175], v[174:175], v[70:71]
	v_pk_add_f32 v[174:175], v[174:175], v[86:87]
	v_pk_add_f32 v[74:75], v[74:75], v[192:193] op_sel:[0,1] op_sel_hi:[1,1] neg_lo:[0,1] neg_hi:[0,1]
	v_pk_add_f32 v[90:91], v[90:91], v[192:193] op_sel:[0,1] op_sel_hi:[1,1] neg_lo:[0,1] neg_hi:[0,1]
	v_exp_f32_e32 v74, v74
	v_exp_f32_e32 v75, v75
	v_exp_f32_e32 v90, v90
	v_exp_f32_e32 v91, v91
	v_pk_add_f32 v[174:175], v[174:175], v[72:73]
	v_pk_add_f32 v[174:175], v[174:175], v[88:89]
	v_pk_add_f32 v[76:77], v[76:77], v[192:193] op_sel:[0,1] op_sel_hi:[1,1] neg_lo:[0,1] neg_hi:[0,1]
	v_pk_add_f32 v[92:93], v[92:93], v[192:193] op_sel:[0,1] op_sel_hi:[1,1] neg_lo:[0,1] neg_hi:[0,1]
	v_exp_f32_e32 v76, v76
	v_exp_f32_e32 v77, v77
	v_exp_f32_e32 v92, v92
	v_exp_f32_e32 v93, v93
	v_pk_add_f32 v[174:175], v[174:175], v[74:75]
	v_pk_add_f32 v[174:175], v[174:175], v[90:91]
	v_pk_add_f32 v[78:79], v[78:79], v[192:193] op_sel:[0,1] op_sel_hi:[1,1] neg_lo:[0,1] neg_hi:[0,1]
	v_pk_add_f32 v[94:95], v[94:95], v[192:193] op_sel:[0,1] op_sel_hi:[1,1] neg_lo:[0,1] neg_hi:[0,1]
	v_exp_f32_e32 v78, v78
	v_exp_f32_e32 v79, v79
	v_exp_f32_e32 v94, v94
	v_exp_f32_e32 v95, v95
	v_pk_add_f32 v[174:175], v[174:175], v[76:77]
	v_pk_add_f32 v[174:175], v[174:175], v[92:93]
	v_pk_add_f32 v[80:81], v[80:81], v[192:193] op_sel:[0,1] op_sel_hi:[1,1] neg_lo:[0,1] neg_hi:[0,1]
	v_pk_add_f32 v[96:97], v[96:97], v[192:193] op_sel:[0,1] op_sel_hi:[1,1] neg_lo:[0,1] neg_hi:[0,1]
	v_exp_f32_e32 v80, v80
	v_exp_f32_e32 v81, v81
	v_exp_f32_e32 v96, v96
	v_exp_f32_e32 v97, v97
	v_pk_add_f32 v[174:175], v[174:175], v[78:79]
	v_pk_add_f32 v[174:175], v[174:175], v[94:95]
	s_nop 0
	v_pk_add_f32 v[174:175], v[174:175], v[80:81]
	v_pk_add_f32 v[174:175], v[174:175], v[96:97]
	v_add_f32_e32 v193, v174, v175
	v_add3_u32 v174, s47, v210, v211
	v_cvt_pk_bf16_f32 v66, v66, v67
	v_cvt_pk_bf16_f32 v67, v68, v69
	v_cvt_pk_bf16_f32 v68, v70, v71
	v_cvt_pk_bf16_f32 v69, v72, v73
	v_cvt_pk_bf16_f32 v70, v74, v75
	v_cvt_pk_bf16_f32 v71, v76, v77
	v_cvt_pk_bf16_f32 v72, v78, v79
	v_cvt_pk_bf16_f32 v73, v80, v81
	v_cvt_pk_bf16_f32 v74, v82, v83
	v_cvt_pk_bf16_f32 v75, v84, v85
	v_cvt_pk_bf16_f32 v76, v86, v87
	v_cvt_pk_bf16_f32 v77, v88, v89
	v_cvt_pk_bf16_f32 v78, v90, v91
	v_cvt_pk_bf16_f32 v79, v92, v93
	v_cvt_pk_bf16_f32 v80, v94, v95
	v_cvt_pk_bf16_f32 v81, v96, v97
	ds_read_b128 v[82:85], v174 offset:17408
	ds_read_b128 v[86:89], v174 offset:22016
	ds_read_b128 v[90:93], v174 offset:26624
	ds_read_b128 v[94:97], v174 offset:31232
	ds_read_b128 v[220:223], v174 offset:17440
	ds_read_b128 v[224:227], v174 offset:22048
	ds_read_b128 v[232:235], v174 offset:26656
	ds_read_b128 v[236:239], v174 offset:31264
	ds_read_b128 v[240:243], v174 offset:17472
	ds_read_b128 v[248:251], v174 offset:22080
	v_fmac_f32_e32 v193, v216, v204
	s_setprio 1
	s_waitcnt lgkmcnt(9)
	v_mfma_f32_32x32x16_bf16 v[50:65], v[82:85], v[66:69], v[50:65]
	ds_read_b128 v[82:85], v174 offset:26688
	s_waitcnt lgkmcnt(9)
	v_mfma_f32_32x32x16_bf16 v[34:49], v[86:89], v[66:69], v[34:49]
	ds_read_b128 v[86:89], v174 offset:31296
	s_waitcnt lgkmcnt(9)
	v_mfma_f32_32x32x16_bf16 v[18:33], v[90:93], v[66:69], v[18:33]
	ds_read_b128 v[90:93], v174 offset:17504
	s_waitcnt lgkmcnt(9)
	v_mfma_f32_32x32x16_bf16 v[2:17], v[94:97], v[66:69], v[2:17]
	ds_read_b128 v[94:97], v174 offset:22112
	s_waitcnt lgkmcnt(9)
	v_mfma_f32_32x32x16_bf16 v[50:65], v[220:223], v[70:73], v[50:65]
	ds_read_b128 v[220:223], v174 offset:26720
	s_waitcnt lgkmcnt(9)
	v_mfma_f32_32x32x16_bf16 v[34:49], v[224:227], v[70:73], v[34:49]
	ds_read_b128 v[224:227], v174 offset:31328
	s_waitcnt lgkmcnt(9)
	v_mfma_f32_32x32x16_bf16 v[18:33], v[232:235], v[70:73], v[18:33]
	s_waitcnt lgkmcnt(8)
	v_mfma_f32_32x32x16_bf16 v[2:17], v[236:239], v[70:73], v[2:17]
	s_waitcnt lgkmcnt(7)
	v_mfma_f32_32x32x16_bf16 v[50:65], v[240:243], v[74:77], v[50:65]
	s_waitcnt lgkmcnt(6)
	v_mfma_f32_32x32x16_bf16 v[34:49], v[248:251], v[74:77], v[34:49]
	s_waitcnt lgkmcnt(5)
	v_mfma_f32_32x32x16_bf16 v[18:33], v[82:85], v[74:77], v[18:33]
	s_waitcnt lgkmcnt(4)
	v_mfma_f32_32x32x16_bf16 v[2:17], v[86:89], v[74:77], v[2:17]
	s_waitcnt lgkmcnt(3)
	v_mfma_f32_32x32x16_bf16 v[50:65], v[90:93], v[78:81], v[50:65]
	s_waitcnt lgkmcnt(2)
	v_mfma_f32_32x32x16_bf16 v[34:49], v[94:97], v[78:81], v[34:49]
	s_waitcnt lgkmcnt(1)
	v_mfma_f32_32x32x16_bf16 v[18:33], v[220:223], v[78:81], v[18:33]
	s_waitcnt lgkmcnt(0)
	v_mfma_f32_32x32x16_bf16 v[2:17], v[224:227], v[78:81], v[2:17]
	s_setprio 0
	v_not_b32_e32 v66, v218
	v_not_b32_e32 v82, v205
	v_bfe_i32 v83, v66, 0, 1
	v_bfe_i32 v174, v82, 0, 1
	v_bfe_i32 v67, v66, 1, 1
	v_bfe_i32 v175, v82, 1, 1
	v_bfe_i32 v68, v66, 2, 1
	v_bfe_i32 v84, v82, 2, 1
	v_bfe_i32 v69, v66, 3, 1
	v_bfe_i32 v85, v82, 3, 1
	v_bfe_i32 v70, v66, 8, 1
	v_bfe_i32 v86, v82, 8, 1
	v_bfe_i32 v71, v66, 9, 1
	v_bfe_i32 v87, v82, 9, 1
	v_bfe_i32 v72, v66, 10, 1
	v_bfe_i32 v88, v82, 10, 1
	v_bfe_i32 v73, v66, 11, 1
	v_bfe_i32 v89, v82, 11, 1
	v_bfe_i32 v74, v66, 16, 1
	v_bfe_i32 v90, v82, 16, 1
	v_bfe_i32 v75, v66, 17, 1
	v_bfe_i32 v91, v82, 17, 1
	v_bfe_i32 v76, v66, 18, 1
	v_bfe_i32 v92, v82, 18, 1
	v_bfe_i32 v77, v66, 19, 1
	v_bfe_i32 v93, v82, 19, 1
	v_bfe_i32 v78, v66, 24, 1
	v_bfe_i32 v94, v82, 24, 1
	v_bfe_i32 v79, v66, 25, 1
	v_bfe_i32 v95, v82, 25, 1
	v_bfe_i32 v80, v66, 26, 1
	v_bfe_i32 v96, v82, 26, 1
	v_bfe_i32 v66, v66, 27, 1
	v_bfe_i32 v82, v82, 27, 1
	s_nop 0
	v_and_b32_e32 v79, 0xff800000, v79
	v_and_b32_e32 v81, 0xff800000, v66
	v_and_b32_e32 v66, 0xff800000, v83
	v_and_b32_e32 v97, 0xff800000, v82
	v_and_b32_e32 v83, 0xff800000, v175
	v_and_b32_e32 v82, 0xff800000, v174
	ds_read_b128 v[174:177], v217 offset:8704
	ds_read_b128 v[218:221], v217
	ds_read_b128 v[222:225], v217 offset:32
	ds_read_b128 v[226:229], v217 offset:8736
	ds_read_b128 v[232:235], v217 offset:64
	ds_read_b128 v[236:239], v217 offset:8768
	ds_read_b128 v[240:243], v217 offset:96
	ds_read_b128 v[248:251], v217 offset:8800
	v_and_b32_e32 v80, 0xff800000, v80
	v_and_b32_e32 v78, 0xff800000, v78
	v_and_b32_e32 v77, 0xff800000, v77
	v_and_b32_e32 v76, 0xff800000, v76
	v_and_b32_e32 v75, 0xff800000, v75
	v_and_b32_e32 v74, 0xff800000, v74
	v_and_b32_e32 v73, 0xff800000, v73
	v_and_b32_e32 v72, 0xff800000, v72
	v_and_b32_e32 v71, 0xff800000, v71
	v_and_b32_e32 v70, 0xff800000, v70
	v_and_b32_e32 v69, 0xff800000, v69
	v_and_b32_e32 v68, 0xff800000, v68
	v_and_b32_e32 v67, 0xff800000, v67
	v_and_b32_e32 v96, 0xff800000, v96
	v_and_b32_e32 v95, 0xff800000, v95
	v_and_b32_e32 v94, 0xff800000, v94
	v_and_b32_e32 v93, 0xff800000, v93
	v_and_b32_e32 v92, 0xff800000, v92
	v_and_b32_e32 v91, 0xff800000, v91
	v_and_b32_e32 v90, 0xff800000, v90
	v_and_b32_e32 v89, 0xff800000, v89
	v_and_b32_e32 v88, 0xff800000, v88
	v_and_b32_e32 v87, 0xff800000, v87
	v_and_b32_e32 v86, 0xff800000, v86
	v_and_b32_e32 v85, 0xff800000, v85
	v_and_b32_e32 v84, 0xff800000, v84
	s_setprio 1
	s_waitcnt lgkmcnt(6)
	v_mfma_f32_32x32x16_bf16 v[66:81], v[218:221], v[98:101], v[66:81]
	v_mfma_f32_32x32x16_bf16 v[82:97], v[174:177], v[98:101], v[82:97]
	s_waitcnt lgkmcnt(5)
	v_mfma_f32_32x32x16_bf16 v[66:81], v[222:225], v[102:105], v[66:81]
	s_waitcnt lgkmcnt(4)
	v_mfma_f32_32x32x16_bf16 v[82:97], v[226:229], v[102:105], v[82:97]
	s_waitcnt lgkmcnt(3)
	v_mfma_f32_32x32x16_bf16 v[66:81], v[232:235], v[106:109], v[66:81]
	s_waitcnt lgkmcnt(2)
	v_mfma_f32_32x32x16_bf16 v[82:97], v[236:239], v[106:109], v[82:97]
	s_waitcnt lgkmcnt(1)
	v_mfma_f32_32x32x16_bf16 v[66:81], v[240:243], v[110:113], v[66:81]
	s_waitcnt lgkmcnt(0)
	v_mfma_f32_32x32x16_bf16 v[82:97], v[248:251], v[110:113], v[82:97]
	s_setprio 0
	ds_read_b128 v[174:177], v217 offset:128
	ds_read_b128 v[218:221], v217 offset:160
	ds_read_b128 v[222:225], v217 offset:8832
	ds_read_b128 v[226:229], v217 offset:8864
	ds_read_b128 v[232:235], v217 offset:192
	ds_read_b128 v[236:239], v217 offset:224
	ds_read_b128 v[240:243], v217 offset:8896
	ds_read_b128 v[248:251], v217 offset:8928
	s_setprio 1
	s_waitcnt lgkmcnt(7)
	v_mfma_f32_32x32x16_bf16 v[66:81], v[174:177], v[114:117], v[66:81]
	s_waitcnt lgkmcnt(5)
	v_mfma_f32_32x32x16_bf16 v[82:97], v[222:225], v[114:117], v[82:97]
	v_mfma_f32_32x32x16_bf16 v[66:81], v[218:221], v[118:121], v[66:81]
	s_waitcnt lgkmcnt(4)
	v_mfma_f32_32x32x16_bf16 v[82:97], v[226:229], v[118:121], v[82:97]
	s_waitcnt lgkmcnt(3)
	v_mfma_f32_32x32x16_bf16 v[66:81], v[232:235], v[122:125], v[66:81]
	s_waitcnt lgkmcnt(1)
	v_mfma_f32_32x32x16_bf16 v[82:97], v[240:243], v[122:125], v[82:97]
	v_mfma_f32_32x32x16_bf16 v[66:81], v[236:239], v[126:129], v[66:81]
	s_waitcnt lgkmcnt(0)
	v_mfma_f32_32x32x16_bf16 v[82:97], v[248:251], v[126:129], v[82:97]
	s_setprio 0
	s_or_b64 exec, exec, s[0:1]
	s_and_b64 vcc, exec, s[8:9]
	s_cbranch_vccz .LBB0_88
	s_branch .LBB0_89
